# grid barrier: last arriving XCD leader bumps every XCD generation word itself (members skip one hop)
# speedup vs baseline: 1.0046x; 1.0046x over previous
.LBB0_596:
	s_andn2_saveexec_b64 s[4:5], s[4:5]
	s_cbranch_execz .LBB0_612
	v_mov_b32_e32 v1, s2
	v_add_co_u32_e32 v2, vcc, 0x3000, v1
	v_mov_b32_e32 v1, s3
	buffer_wbl2 sc1
	s_waitcnt vmcnt(0)
	v_addc_co_u32_e32 v3, vcc, 0, v1, vcc
	v_mov_b32_e32 v1, 1
	flat_atomic_add v1, v[2:3], v1 offset:1024 sc0
	v_cvt_f32_u32_e32 v2, v0
	v_sub_u32_e32 v3, 0, v0
	s_add_u32 s4, s2, 0x3500
	s_addc_u32 s5, s3, 0
	v_rcp_iflag_f32_e32 v2, v2
	s_mov_b64 s[8:9], -1
	v_mul_f32_e32 v2, 0x4f7ffffe, v2
	v_cvt_u32_f32_e32 v2, v2
	v_mul_lo_u32 v3, v3, v2
	v_mul_hi_u32 v3, v2, v3
	v_add_u32_e32 v2, v2, v3
	s_waitcnt vmcnt(0) lgkmcnt(0)
	v_mul_hi_u32 v2, v1, v2
	v_mul_lo_u32 v4, v2, v0
	v_add_u32_e32 v3, 1, v1
	v_sub_u32_e32 v1, v1, v4
	v_add_u32_e32 v5, 1, v2
	v_cmp_ge_u32_e32 vcc, v1, v0
	v_sub_u32_e32 v4, v1, v0
	s_nop 0
	v_cndmask_b32_e32 v2, v2, v5, vcc
	v_cndmask_b32_e32 v1, v1, v4, vcc
	v_add_u32_e32 v4, 1, v2
	v_cmp_ge_u32_e32 vcc, v1, v0
	s_nop 1
	v_cndmask_b32_e32 v2, v2, v4, vcc
	v_mad_u64_u32 v[0:1], s[6:7], v0, v2, v[0:1]
	v_cmp_ne_u32_e32 vcc, v3, v0
	s_cbranch_vccnz .Lxb_notlast_1
	s_sub_u32 s100, s4, 0x1100
	s_subb_u32 s101, s5, 0
	v_mov_b64_e32 v[4:5], s[100:101]
	v_mov_b32_e32 v6, 1
	flat_atomic_add v[4:5], v6
	flat_atomic_add v[4:5], v6 offset:256
	flat_atomic_add v[4:5], v6 offset:512
	flat_atomic_add v[4:5], v6 offset:768
	flat_atomic_add v[4:5], v6 offset:1024
	flat_atomic_add v[4:5], v6 offset:1280
	flat_atomic_add v[4:5], v6 offset:1536
	flat_atomic_add v[4:5], v6 offset:1792
	flat_atomic_add v[4:5], v6 offset:2048
	flat_atomic_add v[4:5], v6 offset:2304
	flat_atomic_add v[4:5], v6 offset:2560
	flat_atomic_add v[4:5], v6 offset:2816
	flat_atomic_add v[4:5], v6 offset:3072
	flat_atomic_add v[4:5], v6 offset:3328
	flat_atomic_add v[4:5], v6 offset:3584
	flat_atomic_add v[4:5], v6 offset:3840
.Lxb_notlast_1:
	v_mov_b64_e32 v[0:1], s[4:5]
	s_and_saveexec_b64 s[6:7], vcc
	s_cbranch_execz .LBB0_609
	v_mov_b64_e32 v[0:1], s[4:5]
	flat_load_dword v0, v[0:1] sc1
	s_mov_b64 s[12:13], 0
	s_waitcnt vmcnt(0) lgkmcnt(0)
	v_cmp_eq_u32_e32 vcc, v0, v2
	s_and_saveexec_b64 s[10:11], vcc
	s_cbranch_execz .LBB0_608
	s_add_u32 s8, s2, 0x200
	s_addc_u32 s9, s3, 0
	s_mov_b32 s25, 1
	s_branch .LBB0_601

.LBB0_611:
	s_or_b64 exec, exec, s[4:5]
	s_add_i32 s4, s24, 0x900
	s_mov_b32 s5, 0
	s_lshl_b64 s[4:5], s[4:5], 2
	s_add_u32 s2, s2, s4
	s_addc_u32 s3, s3, s5
	v_mov_b32_e32 v2, 1
	v_mov_b64_e32 v[0:1], s[2:3]
	s_waitcnt vmcnt(0) lgkmcnt(0)
	s_waitcnt vmcnt(0)

.LBB0_613:
	s_or_b64 exec, exec, s[4:5]
	s_add_i32 s90, s24, 0x900
	s_lshl_b64 s[4:5], s[90:91], 2
	s_add_u32 s4, s36, s4
	s_addc_u32 s5, s37, s5
	v_mov_b64_e32 v[0:1], s[4:5]
	s_waitcnt vmcnt(0) lgkmcnt(0)
	s_waitcnt vmcnt(0)

.LBB0_648:
	s_andn2_saveexec_b64 s[4:5], s[4:5]
	s_cbranch_execz .LBB0_664
	v_mov_b32_e32 v1, s36
	v_add_co_u32_e32 v2, vcc, 0x3000, v1
	v_mov_b32_e32 v1, s37
	buffer_wbl2 sc1
	s_waitcnt vmcnt(0)
	v_addc_co_u32_e32 v3, vcc, 0, v1, vcc
	flat_atomic_add v1, v[2:3], v217 offset:1024 sc0
	v_cvt_f32_u32_e32 v2, v0
	v_sub_u32_e32 v3, 0, v0
	s_add_u32 s4, s36, 0x3500
	s_addc_u32 s5, s37, 0
	v_rcp_iflag_f32_e32 v2, v2
	s_mov_b64 s[8:9], -1
	v_mul_f32_e32 v2, 0x4f7ffffe, v2
	v_cvt_u32_f32_e32 v2, v2
	v_mul_lo_u32 v3, v3, v2
	v_mul_hi_u32 v3, v2, v3
	v_add_u32_e32 v2, v2, v3
	s_waitcnt vmcnt(0) lgkmcnt(0)
	v_mul_hi_u32 v2, v1, v2
	v_mul_lo_u32 v4, v2, v0
	v_add_u32_e32 v3, 1, v1
	v_sub_u32_e32 v1, v1, v4
	v_add_u32_e32 v5, 1, v2
	v_cmp_ge_u32_e32 vcc, v1, v0
	v_sub_u32_e32 v4, v1, v0
	s_nop 0
	v_cndmask_b32_e32 v2, v2, v5, vcc
	v_cndmask_b32_e32 v1, v1, v4, vcc
	v_add_u32_e32 v4, 1, v2
	v_cmp_ge_u32_e32 vcc, v1, v0
	s_nop 1
	v_cndmask_b32_e32 v2, v2, v4, vcc
	v_mad_u64_u32 v[0:1], s[6:7], v0, v2, v[0:1]
	v_cmp_ne_u32_e32 vcc, v3, v0
	s_cbranch_vccnz .Lxb_notlast_2
	s_sub_u32 s100, s4, 0x1100
	s_subb_u32 s101, s5, 0
	v_mov_b64_e32 v[4:5], s[100:101]
	v_mov_b32_e32 v6, 1
	flat_atomic_add v[4:5], v6
	flat_atomic_add v[4:5], v6 offset:256
	flat_atomic_add v[4:5], v6 offset:512
	flat_atomic_add v[4:5], v6 offset:768
	flat_atomic_add v[4:5], v6 offset:1024
	flat_atomic_add v[4:5], v6 offset:1280
	flat_atomic_add v[4:5], v6 offset:1536
	flat_atomic_add v[4:5], v6 offset:1792
	flat_atomic_add v[4:5], v6 offset:2048
	flat_atomic_add v[4:5], v6 offset:2304
	flat_atomic_add v[4:5], v6 offset:2560
	flat_atomic_add v[4:5], v6 offset:2816
	flat_atomic_add v[4:5], v6 offset:3072
	flat_atomic_add v[4:5], v6 offset:3328
	flat_atomic_add v[4:5], v6 offset:3584
	flat_atomic_add v[4:5], v6 offset:3840
.Lxb_notlast_2:
	v_mov_b64_e32 v[0:1], s[4:5]
	s_and_saveexec_b64 s[6:7], vcc
	s_cbranch_execz .LBB0_661
	v_mov_b64_e32 v[0:1], s[4:5]
	flat_load_dword v0, v[0:1] sc1
	s_mov_b64 s[12:13], 0
	s_waitcnt vmcnt(0) lgkmcnt(0)
	v_cmp_eq_u32_e32 vcc, v0, v2
	s_and_saveexec_b64 s[10:11], vcc
	s_cbranch_execz .LBB0_660
	s_add_u32 s8, s36, 0x200
	s_addc_u32 s9, s37, 0
	s_mov_b32 s25, 1
	s_branch .LBB0_653

.LBB0_973:
	s_andn2_saveexec_b64 s[4:5], s[4:5]
	s_cbranch_execz .LBB0_989
	v_mov_b32_e32 v1, s50
	v_add_co_u32_e32 v2, vcc, 0x3000, v1
	v_mov_b32_e32 v1, s51
	buffer_wbl2 sc1
	s_waitcnt vmcnt(0)
	v_addc_co_u32_e32 v3, vcc, 0, v1, vcc
	flat_atomic_add v1, v[2:3], v217 offset:1024 sc0
	v_cvt_f32_u32_e32 v2, v0
	v_sub_u32_e32 v3, 0, v0
	s_mov_b64 s[8:9], -1
	v_rcp_iflag_f32_e32 v2, v2
	s_nop 0
	v_mul_f32_e32 v2, 0x4f7ffffe, v2
	v_cvt_u32_f32_e32 v2, v2
	v_mul_lo_u32 v3, v3, v2
	v_mul_hi_u32 v3, v2, v3
	v_add_u32_e32 v2, v2, v3
	s_waitcnt vmcnt(0) lgkmcnt(0)
	v_mul_hi_u32 v2, v1, v2
	v_mul_lo_u32 v3, v2, v0
	v_sub_u32_e32 v3, v1, v3
	v_cmp_ge_u32_e32 vcc, v3, v0
	v_add_u32_e32 v4, 1, v2
	s_nop 0
	v_cndmask_b32_e32 v2, v2, v4, vcc
	v_sub_u32_e32 v4, v3, v0
	v_cndmask_b32_e32 v3, v3, v4, vcc
	v_cmp_ge_u32_e32 vcc, v3, v0
	v_add_u32_e32 v3, 1, v2
	s_nop 0
	v_cndmask_b32_e32 v2, v2, v3, vcc
	v_add_u32_e32 v3, 1, v1
	v_mad_u64_u32 v[0:1], s[4:5], v0, v2, v[0:1]
	s_add_u32 s4, s50, 0x3500
	s_addc_u32 s5, s51, 0
	v_cmp_ne_u32_e32 vcc, v3, v0
	s_cbranch_vccnz .Lxb_notlast_3
	s_sub_u32 s100, s4, 0x1100
	s_subb_u32 s101, s5, 0
	v_mov_b64_e32 v[4:5], s[100:101]
	v_mov_b32_e32 v6, 1
	flat_atomic_add v[4:5], v6
	flat_atomic_add v[4:5], v6 offset:256
	flat_atomic_add v[4:5], v6 offset:512
	flat_atomic_add v[4:5], v6 offset:768
	flat_atomic_add v[4:5], v6 offset:1024
	flat_atomic_add v[4:5], v6 offset:1280
	flat_atomic_add v[4:5], v6 offset:1536
	flat_atomic_add v[4:5], v6 offset:1792
	flat_atomic_add v[4:5], v6 offset:2048
	flat_atomic_add v[4:5], v6 offset:2304
	flat_atomic_add v[4:5], v6 offset:2560
	flat_atomic_add v[4:5], v6 offset:2816
	flat_atomic_add v[4:5], v6 offset:3072
	flat_atomic_add v[4:5], v6 offset:3328
	flat_atomic_add v[4:5], v6 offset:3584
	flat_atomic_add v[4:5], v6 offset:3840
.Lxb_notlast_3:
	v_mov_b64_e32 v[0:1], s[4:5]
	s_and_saveexec_b64 s[6:7], vcc
	s_cbranch_execz .LBB0_986
	v_mov_b64_e32 v[0:1], s[4:5]
	flat_load_dword v0, v[0:1] sc1
	s_mov_b64 s[12:13], 0
	s_waitcnt vmcnt(0) lgkmcnt(0)
	v_cmp_eq_u32_e32 vcc, v0, v2
	s_and_saveexec_b64 s[10:11], vcc
	s_cbranch_execz .LBB0_985
	s_add_u32 s8, s50, 0x200
	s_addc_u32 s9, s51, 0
	s_mov_b32 s25, 1
	s_branch .LBB0_978

.LBB0_988:
	s_or_b64 exec, exec, s[4:5]
	s_add_i32 s90, s24, 0x900
	s_lshl_b64 s[4:5], s[90:91], 2
	s_add_u32 s4, s50, s4
	s_addc_u32 s5, s51, s5
	v_mov_b64_e32 v[0:1], s[4:5]
	s_waitcnt vmcnt(0) lgkmcnt(0)
	s_waitcnt vmcnt(0)

.LBB0_1302:
	s_andn2_saveexec_b64 s[4:5], s[4:5]
	s_cbranch_execz .LBB0_1318
	v_mov_b32_e32 v1, s56
	v_add_co_u32_e32 v2, vcc, 0x3000, v1
	v_mov_b32_e32 v1, s57
	buffer_wbl2 sc1
	s_waitcnt vmcnt(0)
	v_addc_co_u32_e32 v3, vcc, 0, v1, vcc
	flat_atomic_add v1, v[2:3], v217 offset:1024 sc0
	v_cvt_f32_u32_e32 v2, v0
	v_sub_u32_e32 v3, 0, v0
	s_mov_b64 s[8:9], -1
	v_rcp_iflag_f32_e32 v2, v2
	s_nop 0
	v_mul_f32_e32 v2, 0x4f7ffffe, v2
	v_cvt_u32_f32_e32 v2, v2
	v_mul_lo_u32 v3, v3, v2
	v_mul_hi_u32 v3, v2, v3
	v_add_u32_e32 v2, v2, v3
	s_waitcnt vmcnt(0) lgkmcnt(0)
	v_mul_hi_u32 v2, v1, v2
	v_mul_lo_u32 v3, v2, v0
	v_sub_u32_e32 v3, v1, v3
	v_cmp_ge_u32_e32 vcc, v3, v0
	v_add_u32_e32 v4, 1, v2
	s_nop 0
	v_cndmask_b32_e32 v2, v2, v4, vcc
	v_sub_u32_e32 v4, v3, v0
	v_cndmask_b32_e32 v3, v3, v4, vcc
	v_cmp_ge_u32_e32 vcc, v3, v0
	v_add_u32_e32 v3, 1, v2
	s_nop 0
	v_cndmask_b32_e32 v2, v2, v3, vcc
	v_add_u32_e32 v3, 1, v1
	v_mad_u64_u32 v[0:1], s[4:5], v0, v2, v[0:1]
	s_add_u32 s4, s56, 0x3500
	s_addc_u32 s5, s57, 0
	v_cmp_ne_u32_e32 vcc, v3, v0
	s_cbranch_vccnz .Lxb_notlast_7
	s_sub_u32 s100, s4, 0x1100
	s_subb_u32 s101, s5, 0
	v_mov_b64_e32 v[4:5], s[100:101]
	v_mov_b32_e32 v6, 1
	flat_atomic_add v[4:5], v6
	flat_atomic_add v[4:5], v6 offset:256
	flat_atomic_add v[4:5], v6 offset:512
	flat_atomic_add v[4:5], v6 offset:768
	flat_atomic_add v[4:5], v6 offset:1024
	flat_atomic_add v[4:5], v6 offset:1280
	flat_atomic_add v[4:5], v6 offset:1536
	flat_atomic_add v[4:5], v6 offset:1792
	flat_atomic_add v[4:5], v6 offset:2048
	flat_atomic_add v[4:5], v6 offset:2304
	flat_atomic_add v[4:5], v6 offset:2560
	flat_atomic_add v[4:5], v6 offset:2816
	flat_atomic_add v[4:5], v6 offset:3072
	flat_atomic_add v[4:5], v6 offset:3328
	flat_atomic_add v[4:5], v6 offset:3584
	flat_atomic_add v[4:5], v6 offset:3840
.Lxb_notlast_7:
	v_mov_b64_e32 v[0:1], s[4:5]
	s_and_saveexec_b64 s[6:7], vcc
	s_cbranch_execz .LBB0_1315
	v_mov_b64_e32 v[0:1], s[4:5]
	flat_load_dword v0, v[0:1] sc1
	s_mov_b64 s[12:13], 0
	s_waitcnt vmcnt(0) lgkmcnt(0)
	v_cmp_eq_u32_e32 vcc, v0, v2
	s_and_saveexec_b64 s[10:11], vcc
	s_cbranch_execz .LBB0_1314
	s_add_u32 s8, s56, 0x200
	s_addc_u32 s9, s57, 0
	s_mov_b32 s25, 1
	s_branch .LBB0_1307

.LBB0_1317:
	s_or_b64 exec, exec, s[4:5]
	s_add_i32 s4, s24, 0x900
	s_mov_b32 s5, s91
	s_lshl_b64 s[4:5], s[4:5], 2
	s_add_u32 s4, s56, s4
	s_addc_u32 s5, s57, s5
	v_mov_b64_e32 v[0:1], s[4:5]
	s_waitcnt vmcnt(0) lgkmcnt(0)
	s_waitcnt vmcnt(0)

.LBB0_1730:
	s_andn2_saveexec_b64 s[4:5], s[4:5]
	s_cbranch_execz .LBB0_1746
	v_mov_b32_e32 v1, s46
	v_add_co_u32_e32 v2, vcc, 0x3000, v1
	v_mov_b32_e32 v1, s47
	buffer_wbl2 sc1
	s_waitcnt vmcnt(0)
	v_addc_co_u32_e32 v3, vcc, 0, v1, vcc
	flat_atomic_add v1, v[2:3], v217 offset:1024 sc0
	v_cvt_f32_u32_e32 v2, v0
	v_sub_u32_e32 v3, 0, v0
	s_mov_b64 s[10:11], -1
	v_rcp_iflag_f32_e32 v2, v2
	s_nop 0
	v_mul_f32_e32 v2, 0x4f7ffffe, v2
	v_cvt_u32_f32_e32 v2, v2
	v_mul_lo_u32 v3, v3, v2
	v_mul_hi_u32 v3, v2, v3
	v_add_u32_e32 v2, v2, v3
	s_waitcnt vmcnt(0) lgkmcnt(0)
	v_mul_hi_u32 v2, v1, v2
	v_mul_lo_u32 v3, v2, v0
	v_sub_u32_e32 v3, v1, v3
	v_cmp_ge_u32_e32 vcc, v3, v0
	v_add_u32_e32 v4, 1, v2
	s_nop 0
	v_cndmask_b32_e32 v2, v2, v4, vcc
	v_sub_u32_e32 v4, v3, v0
	v_cndmask_b32_e32 v3, v3, v4, vcc
	v_cmp_ge_u32_e32 vcc, v3, v0
	v_add_u32_e32 v3, 1, v2
	s_nop 0
	v_cndmask_b32_e32 v2, v2, v3, vcc
	v_add_u32_e32 v3, 1, v1
	v_mad_u64_u32 v[0:1], s[4:5], v0, v2, v[0:1]
	s_add_u32 s4, s46, 0x3500
	s_addc_u32 s5, s47, 0
	v_cmp_ne_u32_e32 vcc, v3, v0
	s_cbranch_vccnz .Lxb_notlast_9
	s_sub_u32 s100, s4, 0x1100
	s_subb_u32 s101, s5, 0
	v_mov_b64_e32 v[4:5], s[100:101]
	v_mov_b32_e32 v6, 1
	flat_atomic_add v[4:5], v6
	flat_atomic_add v[4:5], v6 offset:256
	flat_atomic_add v[4:5], v6 offset:512
	flat_atomic_add v[4:5], v6 offset:768
	flat_atomic_add v[4:5], v6 offset:1024
	flat_atomic_add v[4:5], v6 offset:1280
	flat_atomic_add v[4:5], v6 offset:1536
	flat_atomic_add v[4:5], v6 offset:1792
	flat_atomic_add v[4:5], v6 offset:2048
	flat_atomic_add v[4:5], v6 offset:2304
	flat_atomic_add v[4:5], v6 offset:2560
	flat_atomic_add v[4:5], v6 offset:2816
	flat_atomic_add v[4:5], v6 offset:3072
	flat_atomic_add v[4:5], v6 offset:3328
	flat_atomic_add v[4:5], v6 offset:3584
	flat_atomic_add v[4:5], v6 offset:3840
.Lxb_notlast_9:
	v_mov_b64_e32 v[0:1], s[4:5]
	s_and_saveexec_b64 s[6:7], vcc
	s_cbranch_execz .LBB0_1743
	v_mov_b64_e32 v[0:1], s[4:5]
	flat_load_dword v0, v[0:1] sc1
	s_mov_b64 s[14:15], 0
	s_waitcnt vmcnt(0) lgkmcnt(0)
	v_cmp_eq_u32_e32 vcc, v0, v2
	s_and_saveexec_b64 s[12:13], vcc
	s_cbranch_execz .LBB0_1742
	s_add_u32 s10, s46, 0x200
	s_addc_u32 s11, s47, 0
	s_mov_b32 s9, 1
	s_branch .LBB0_1735

.LBB0_1745:
	s_or_b64 exec, exec, s[4:5]
	s_add_i32 s4, s8, 0x900
	s_mov_b32 s5, s91
	s_lshl_b64 s[4:5], s[4:5], 2
	s_add_u32 s4, s46, s4
	s_addc_u32 s5, s47, s5
	v_mov_b64_e32 v[0:1], s[4:5]
	s_waitcnt vmcnt(0) lgkmcnt(0)
	s_waitcnt vmcnt(0)

.LBB0_1842:
	v_mov_b32_e32 v1, s36
	v_add_co_u32_e32 v2, vcc, 0x3000, v1
	v_mov_b32_e32 v1, s37
	buffer_wbl2 sc1
	s_waitcnt vmcnt(0)
	v_addc_co_u32_e32 v3, vcc, 0, v1, vcc
	flat_atomic_add v1, v[2:3], v217 offset:1024 sc0
	v_cvt_f32_u32_e32 v2, v0
	v_sub_u32_e32 v3, 0, v0
	s_mov_b64 s[8:9], -1
	v_rcp_iflag_f32_e32 v2, v2
	s_nop 0
	v_mul_f32_e32 v2, 0x4f7ffffe, v2
	v_cvt_u32_f32_e32 v2, v2
	v_mul_lo_u32 v3, v3, v2
	v_mul_hi_u32 v3, v2, v3
	v_add_u32_e32 v2, v2, v3
	s_waitcnt vmcnt(0) lgkmcnt(0)
	v_mul_hi_u32 v2, v1, v2
	v_mul_lo_u32 v3, v2, v0
	v_sub_u32_e32 v3, v1, v3
	v_cmp_ge_u32_e32 vcc, v3, v0
	v_add_u32_e32 v4, 1, v2
	s_nop 0
	v_cndmask_b32_e32 v2, v2, v4, vcc
	v_sub_u32_e32 v4, v3, v0
	v_cndmask_b32_e32 v3, v3, v4, vcc
	v_cmp_ge_u32_e32 vcc, v3, v0
	v_add_u32_e32 v3, 1, v2
	s_nop 0
	v_cndmask_b32_e32 v2, v2, v3, vcc
	v_add_u32_e32 v3, 1, v1
	v_mad_u64_u32 v[0:1], s[4:5], v0, v2, v[0:1]
	s_add_u32 s4, s36, 0x3500
	s_addc_u32 s5, s37, 0
	v_cmp_ne_u32_e32 vcc, v3, v0
	s_cbranch_vccnz .Lxb_notlast_10
	s_sub_u32 s100, s4, 0x1100
	s_subb_u32 s101, s5, 0
	v_mov_b64_e32 v[4:5], s[100:101]
	v_mov_b32_e32 v6, 1
	flat_atomic_add v[4:5], v6
	flat_atomic_add v[4:5], v6 offset:256
	flat_atomic_add v[4:5], v6 offset:512
	flat_atomic_add v[4:5], v6 offset:768
	flat_atomic_add v[4:5], v6 offset:1024
	flat_atomic_add v[4:5], v6 offset:1280
	flat_atomic_add v[4:5], v6 offset:1536
	flat_atomic_add v[4:5], v6 offset:1792
	flat_atomic_add v[4:5], v6 offset:2048
	flat_atomic_add v[4:5], v6 offset:2304
	flat_atomic_add v[4:5], v6 offset:2560
	flat_atomic_add v[4:5], v6 offset:2816
	flat_atomic_add v[4:5], v6 offset:3072
	flat_atomic_add v[4:5], v6 offset:3328
	flat_atomic_add v[4:5], v6 offset:3584
	flat_atomic_add v[4:5], v6 offset:3840
